# LayerNorm phases: waves 1-7 parked at the grid barrier touch (load into dummy VGPRs) their first-iteration XN/XL rows (x rows for the first LN) so they are L2-resident at phase start
# baseline (speedup 1.0000x reference)
.LBB0_322:
	s_or_b64 exec, exec, s[8:9]
	s_waitcnt vmcnt(0)
	s_branch .LBB0_323
.Ltouch_0:
	s_mov_b64 exec, -1
	s_lshl_b32 s98, s33, 14
	s_add_u32 s98, s16, s98
	s_addc_u32 s99, s17, 0
	v_lshlrev_b32_e32 v226, 4, v180
	global_load_dwordx4 v[222:225], v226, s[98:99]
	global_load_dwordx4 v[222:225], v226, s[98:99] offset:1024
	global_load_dwordx4 v[222:225], v226, s[98:99] offset:2048
	global_load_dwordx4 v[222:225], v226, s[98:99] offset:3072
	s_add_u32 s98, s98, 0x1000
	s_addc_u32 s99, s99, 0
	global_load_dwordx4 v[222:225], v226, s[98:99]
	global_load_dwordx4 v[222:225], v226, s[98:99] offset:1024
	global_load_dwordx4 v[222:225], v226, s[98:99] offset:2048
	global_load_dwordx4 v[222:225], v226, s[98:99] offset:3072
	s_add_u32 s98, s98, 0x1000
	s_addc_u32 s99, s99, 0
	global_load_dwordx4 v[222:225], v226, s[98:99]
	global_load_dwordx4 v[222:225], v226, s[98:99] offset:1024
	global_load_dwordx4 v[222:225], v226, s[98:99] offset:2048
	global_load_dwordx4 v[222:225], v226, s[98:99] offset:3072
	s_add_u32 s98, s98, 0x1000
	s_addc_u32 s99, s99, 0
	global_load_dwordx4 v[222:225], v226, s[98:99]
	global_load_dwordx4 v[222:225], v226, s[98:99] offset:1024
	global_load_dwordx4 v[222:225], v226, s[98:99] offset:2048
	global_load_dwordx4 v[222:225], v226, s[98:99] offset:3072

.LBB0_659:
	s_or_b64 exec, exec, s[10:11]
	s_waitcnt vmcnt(0)
	s_branch .LBB0_660
.Ltouch_1:
	s_mov_b64 exec, -1
	s_lshl_b32 s98, s33, 13
	s_add_u32 s98, s40, s98
	s_addc_u32 s99, s41, 0
	s_add_u32 s98, s98, 0x7000000
	s_addc_u32 s99, s99, 0
	s_lshl_b32 s100, s33, 11
	s_add_u32 s100, s40, s100
	s_addc_u32 s101, s41, 0
	s_add_u32 s100, s100, 0x1b400000
	s_addc_u32 s101, s101, 0
	v_lshlrev_b32_e32 v226, 4, v180
	v_add_u32_e32 v227, 0x1000, v226
	global_load_dwordx4 v[222:225], v226, s[98:99]
	global_load_dwordx4 v[222:225], v226, s[98:99] offset:1024
	global_load_dwordx4 v[222:225], v226, s[98:99] offset:2048
	global_load_dwordx4 v[222:225], v226, s[98:99] offset:3072
	global_load_dwordx4 v[222:225], v227, s[98:99]
	global_load_dwordx4 v[222:225], v227, s[98:99] offset:1024
	global_load_dwordx4 v[222:225], v227, s[98:99] offset:2048
	global_load_dwordx4 v[222:225], v227, s[98:99] offset:3072
	global_load_dwordx4 v[222:225], v226, s[100:101]
	global_load_dwordx4 v[222:225], v226, s[100:101] offset:1024

.LBB0_862:
	s_or_b64 exec, exec, s[16:17]
	s_waitcnt vmcnt(0)
	s_branch .LBB0_863

	.amdhsa_kernel _Z8yoco_fwd4Args
		.amdhsa_group_segment_fixed_size 0
		.amdhsa_private_segment_fixed_size 0
		.amdhsa_kernarg_size 376
		.amdhsa_user_sgpr_count 2
		.amdhsa_user_sgpr_dispatch_ptr 0
		.amdhsa_user_sgpr_queue_ptr 0
		.amdhsa_user_sgpr_kernarg_segment_ptr 1
		.amdhsa_user_sgpr_dispatch_id 0
		.amdhsa_user_sgpr_kernarg_preload_length 0
		.amdhsa_user_sgpr_kernarg_preload_offset 0
		.amdhsa_user_sgpr_private_segment_size 0
		.amdhsa_uses_dynamic_stack 0
		.amdhsa_enable_private_segment 0
		.amdhsa_system_sgpr_workgroup_id_x 1
		.amdhsa_system_sgpr_workgroup_id_y 0
		.amdhsa_system_sgpr_workgroup_id_z 0
		.amdhsa_system_sgpr_workgroup_info 0
		.amdhsa_system_vgpr_workitem_id 2
		.amdhsa_next_free_vgpr 231
		.amdhsa_next_free_sgpr 102
		.amdhsa_accum_offset 232
		.amdhsa_reserve_vcc 1
		.amdhsa_float_round_mode_32 0
		.amdhsa_float_round_mode_16_64 0
		.amdhsa_float_denorm_mode_32 3
		.amdhsa_float_denorm_mode_16_64 3
		.amdhsa_dx10_clamp 1
		.amdhsa_ieee_mode 1
		.amdhsa_fp16_overflow 0
		.amdhsa_tg_split 0
		.amdhsa_exception_fp_ieee_invalid_op 0
		.amdhsa_exception_fp_denorm_src 0
		.amdhsa_exception_fp_ieee_div_zero 0
		.amdhsa_exception_fp_ieee_overflow 0
		.amdhsa_exception_fp_ieee_underflow 0
		.amdhsa_exception_fp_ieee_inexact 0
		.amdhsa_exception_int_div_zero 0
	.end_amdhsa_kernel

amdhsa.kernels:
  - .agpr_count:     0
    .args:
      - .offset:         0
        .size:           120
        .value_kind:     by_value
      - .offset:         120
        .size:           4
        .value_kind:     hidden_block_count_x
      - .offset:         124
        .size:           4
        .value_kind:     hidden_block_count_y
      - .offset:         128
        .size:           4
        .value_kind:     hidden_block_count_z
      - .offset:         132
        .size:           2
        .value_kind:     hidden_group_size_x
      - .offset:         134
        .size:           2
        .value_kind:     hidden_group_size_y
      - .offset:         136
        .size:           2
        .value_kind:     hidden_group_size_z
      - .offset:         138
        .size:           2
        .value_kind:     hidden_remainder_x
      - .offset:         140
        .size:           2
        .value_kind:     hidden_remainder_y
      - .offset:         142
        .size:           2
        .value_kind:     hidden_remainder_z
      - .offset:         160
        .size:           8
        .value_kind:     hidden_global_offset_x
      - .offset:         168
        .size:           8
        .value_kind:     hidden_global_offset_y
      - .offset:         176
        .size:           8
        .value_kind:     hidden_global_offset_z
      - .offset:         184
        .size:           2
        .value_kind:     hidden_grid_dims
      - .offset:         208
        .size:           8
        .value_kind:     hidden_multigrid_sync_arg
      - .offset:         240
        .size:           4
        .value_kind:     hidden_dynamic_lds_size
    .group_segment_fixed_size: 0
    .kernarg_segment_align: 8
    .kernarg_segment_size: 376
    .language:       OpenCL C
    .language_version:
      - 2
      - 0
    .max_flat_workgroup_size: 512
    .name:           _Z8yoco_fwd4Args
    .private_segment_fixed_size: 0
    .sgpr_count:     108
    .sgpr_spill_count: 3
    .symbol:         _Z8yoco_fwd4Args.kd
    .uniform_work_group_size: 1
    .uses_dynamic_stack: false
    .vgpr_count:     231
    .vgpr_spill_count: 0
    .wavefront_size: 64
